# v50 + qint:3 (P2a queue interleave: WGs with bit3 set drain attention queue before late-weights queue)
# speedup vs baseline: 1.0052x; 1.0052x over previous
.LBB0_478:
	v_readlane_b32 s98, v254, 15
	s_nop 0
	s_bitcmp1_b32 s98, 3
	s_cselect_b32 s98, 1, 0
	s_cbranch_scc1 .LBB0_516

.Lqi_lwdone:
	s_cmp_eq_u32 s98, 2
	s_cbranch_scc1 .LBB0_536

.Lqi_attdone:
	s_cmp_lg_u32 s98, 1
	s_cbranch_scc1 .LBB0_536
	s_mov_b32 s98, 2
	s_branch .Lqi_lw
